# layer-0 norm_rows loop: the three later modulation (scale, shift) load pairs hoisted to the loop top, 4 serialized round trips per row become 1
# speedup vs baseline: 1.0091x; 1.0091x over previous
; __device__ __forceinline__ unsigned pk2(float lo, float hi) { f32x2_t v = {lo, hi}; bf16x2_t b = __builtin_convertvector(v, bf16x2_t); return __builtin_bit_cast(unsigned, b); }
; __device__ __forceinline__ void norm_rows(const float* x, const float* g, const float* modl  , int sh_off, int sc_off, bf16_t* h, int gw, int ngw, int lane) {
;     ...
;     for (int row = gw; row < M; row += ngw) {
;         const f32x4* xr = (const f32x4*)(x + (size_t)row * DM) + lane;
;         f32x4 v[4]; float ss = 0.f;
; #pragma unroll
;         for (int j = 0; j < 4; ++j) { v[j] = xr[64 * j]; ss += (v[j].x * v[j].x + v[j].y * v[j].y) + (v[j].z * v[j].z + v[j].w * v[j].w); }
;         const float rstd = 1.0f / sqrtf(wave_sum(ss) * (1.0f / DM) + NORM_EPS);
;         const float* mb = modl + (size_t)(row >> 11) * 6 * DM;
;         unsigned long long* o8 = (unsigned long long*)(h + (size_t)row * DM) + lane;
; #pragma unroll
;         for (int j = 0; j < 4; ++j) {
;             const f32x4 sc = *((const f32x4*)(mb + sc_off) + lane + 64 * j), sh = *((const f32x4*)(mb + sh_off) + lane + 64 * j);
;             const f32x4 y = v[j] * rstd * gv[j] * (sc + 1.0f) + sh;
;             o8[64 * j] = (unsigned long long)pk2(y.x, y.y) | ((unsigned long long)pk2(y.z, y.w) << 32);
;         }
.LBB0_691:
	global_load_dwordx4 v[24:27], v[22:23], off offset:-3072
	global_load_dwordx4 v[28:31], v[22:23], off offset:-2048
	global_load_dwordx4 v[32:35], v[22:23], off offset:-1024
	global_load_dwordx4 v[16:19], v[22:23], off
	s_ashr_i32 s0, s2, 11
	s_mul_i32 s0, s0, 6
	s_ashr_i32 s1, s0, 31
	s_lshl_b64 s[0:1], s[0:1], 12
	s_add_u32 s0, s7, s0
	s_addc_u32 s1, s35, s1
	v_lshl_add_u64 v[44:45], s[0:1], 0, v[64:65]
	s_mov_b64 s[0:1], 0x1000
	v_lshl_add_u64 v[46:47], v[44:45], 0, s[0:1]
	s_movk_i32 s0, 0x1000
	v_add_co_u32_e32 v40, vcc, s0, v44
	s_add_i32 s2, s2, s6
	s_nop 0
	v_addc_co_u32_e32 v41, vcc, 0, v45, vcc
	flat_load_dwordx4 v[36:39], v[44:45]
	s_nop 0
	flat_load_dwordx4 v[40:43], v[40:41]
	flat_load_dwordx4 v[100:103], v[46:47] offset:1024
	flat_load_dwordx4 v[104:107], v[44:45] offset:1024
	flat_load_dwordx4 v[108:111], v[46:47] offset:2048
	flat_load_dwordx4 v[112:115], v[44:45] offset:2048
	flat_load_dwordx4 v[116:119], v[46:47] offset:3072
	flat_load_dwordx4 v[120:123], v[44:45] offset:3072
	v_lshl_add_u64 v[22:23], v[22:23], 0, s[8:9]
	s_cmpk_gt_i32 s2, 0x3fff
	s_waitcnt vmcnt(0)
	v_mul_f32_e32 v48, v25, v25
	v_mul_f32_e32 v49, v27, v27
	v_mul_f32_e32 v50, v29, v29
	v_mul_f32_e32 v51, v31, v31
	v_mul_f32_e32 v52, v33, v33
	v_mul_f32_e32 v53, v35, v35
	v_fmac_f32_e32 v48, v24, v24
	v_fmac_f32_e32 v49, v26, v26
	v_fmac_f32_e32 v50, v28, v28
	v_fmac_f32_e32 v51, v30, v30
	v_mul_f32_e32 v54, v17, v17
	v_mul_f32_e32 v55, v19, v19
	v_fmac_f32_e32 v52, v32, v32
	v_fmac_f32_e32 v53, v34, v34
	v_add_f32_e32 v48, v48, v49
	v_add_f32_e32 v49, v50, v51
	v_fmac_f32_e32 v54, v16, v16
	v_fmac_f32_e32 v55, v18, v18
	v_add_f32_e32 v50, v52, v53
	v_add_f32_e32 v48, v48, v49
	v_add_f32_e32 v51, v54, v55
	v_add_f32_e32 v48, v48, v50
	v_add_f32_e32 v48, v48, v51
	ds_swizzle_b32 v49, v48 offset:swizzle(SWAP,1)
	s_waitcnt lgkmcnt(0)
	v_pk_add_f32 v[42:43], v[42:43], 1.0 op_sel_hi:[1,0]
	v_pk_add_f32 v[40:41], v[40:41], 1.0 op_sel_hi:[1,0]
	v_add_f32_e32 v48, v48, v49
	ds_swizzle_b32 v49, v48 offset:swizzle(SWAP,2)
	s_waitcnt lgkmcnt(0)
	v_add_f32_e32 v48, v48, v49
	ds_swizzle_b32 v49, v48 offset:swizzle(SWAP,4)
	s_waitcnt lgkmcnt(0)
	v_add_f32_e32 v48, v48, v49
	ds_swizzle_b32 v49, v48 offset:swizzle(SWAP,8)
	s_waitcnt lgkmcnt(0)
	v_add_f32_e32 v48, v48, v49
	ds_swizzle_b32 v49, v48 offset:swizzle(SWAP,16)
	s_waitcnt lgkmcnt(0)
	v_add_f32_e32 v48, v48, v49
	v_mov_b32_e32 v49, v48
	s_nop 1
	v_permlane32_swap_b32_e32 v48, v49
	v_add_f32_e32 v48, v48, v49
	v_fmamk_f32 v48, v48, 0x3a800000, v242
	v_mul_f32_e32 v49, 0x4f800000, v48
	v_cmp_gt_f32_e32 vcc, s3, v48
	s_nop 1
	v_cndmask_b32_e32 v48, v48, v49, vcc
	v_sqrt_f32_e32 v49, v48
	s_nop 0
	v_add_u32_e32 v50, -1, v49
	v_add_u32_e32 v51, 1, v49
	v_fma_f32 v52, -v50, v49, v48
	v_fma_f32 v53, -v51, v49, v48
	v_cmp_ge_f32_e64 s[0:1], 0, v52
	s_nop 1
	v_cndmask_b32_e64 v49, v49, v50, s[0:1]
	v_cmp_lt_f32_e64 s[0:1], 0, v53
	s_nop 1
	v_cndmask_b32_e64 v49, v49, v51, s[0:1]
	v_mul_f32_e32 v50, 0x37800000, v49
	v_cndmask_b32_e32 v49, v49, v50, vcc
	v_cmp_class_f32_e32 vcc, v48, v245
	s_nop 1
	v_cndmask_b32_e32 v48, v49, v48, vcc
	v_div_scale_f32 v49, s[0:1], v48, v48, 1.0
	v_rcp_f32_e32 v51, v49
	v_div_scale_f32 v50, vcc, 1.0, v48, 1.0
	v_fma_f32 v52, -v49, v51, 1.0
	v_fmac_f32_e32 v51, v52, v51
	v_mul_f32_e32 v52, v50, v51
	v_fma_f32 v53, -v49, v52, v50
	v_fmac_f32_e32 v52, v53, v51
	v_fma_f32 v49, -v49, v52, v50
	v_div_fmas_f32 v49, v49, v51, v52
	v_div_fixup_f32 v48, v49, v48, 1.0
	v_pk_mul_f32 v[26:27], v[26:27], v[48:49] op_sel_hi:[1,0]
	v_pk_mul_f32 v[24:25], v[24:25], v[48:49] op_sel_hi:[1,0]
	v_pk_mul_f32 v[26:27], v[2:3], v[26:27]
	v_pk_mul_f32 v[24:25], v[0:1], v[24:25]
	v_pk_fma_f32 v[26:27], v[42:43], v[26:27], v[38:39]
	v_pk_fma_f32 v[24:25], v[40:41], v[24:25], v[36:37]
	v_pk_mul_f32 v[30:31], v[30:31], v[48:49] op_sel_hi:[1,0]
	v_cvt_pk_bf16_f32 v24, v24, v25
	v_cvt_pk_bf16_f32 v25, v26, v27
	flat_store_dwordx2 v[20:21], v[24:25]
	s_nop 0
	v_pk_mul_f32 v[28:29], v[28:29], v[48:49] op_sel_hi:[1,0]
	v_pk_mul_f32 v[30:31], v[6:7], v[30:31]
	v_pk_mul_f32 v[28:29], v[4:5], v[28:29]
	v_pk_mul_f32 v[34:35], v[34:35], v[48:49] op_sel_hi:[1,0]
	v_pk_mul_f32 v[32:33], v[32:33], v[48:49] op_sel_hi:[1,0]
	v_pk_mul_f32 v[34:35], v[10:11], v[34:35]
	v_pk_mul_f32 v[32:33], v[8:9], v[32:33]
	v_pk_mul_f32 v[18:19], v[18:19], v[48:49] op_sel_hi:[1,0]
	v_pk_mul_f32 v[16:17], v[16:17], v[48:49] op_sel_hi:[1,0]
	v_pk_mul_f32 v[18:19], v[14:15], v[18:19]
	v_pk_mul_f32 v[16:17], v[12:13], v[16:17]
	v_pk_add_f32 v[26:27], v[102:103], 1.0 op_sel_hi:[1,0]
	v_pk_add_f32 v[24:25], v[100:101], 1.0 op_sel_hi:[1,0]
	v_pk_fma_f32 v[26:27], v[26:27], v[30:31], v[106:107]
	v_pk_fma_f32 v[24:25], v[24:25], v[28:29], v[104:105]
	s_nop 0
	v_cvt_pk_bf16_f32 v24, v24, v25
	v_cvt_pk_bf16_f32 v25, v26, v27
	flat_store_dwordx2 v[20:21], v[24:25] offset:512
	s_nop 0
	v_pk_add_f32 v[26:27], v[110:111], 1.0 op_sel_hi:[1,0]
	v_pk_add_f32 v[24:25], v[108:109], 1.0 op_sel_hi:[1,0]
	v_pk_fma_f32 v[26:27], v[26:27], v[34:35], v[114:115]
	v_pk_fma_f32 v[24:25], v[24:25], v[32:33], v[112:113]
	s_nop 0
	v_cvt_pk_bf16_f32 v24, v24, v25
	v_cvt_pk_bf16_f32 v25, v26, v27
	flat_store_dwordx2 v[20:21], v[24:25] offset:1024
	s_nop 0
	v_pk_add_f32 v[26:27], v[118:119], 1.0 op_sel_hi:[1,0]
	v_pk_add_f32 v[24:25], v[116:117], 1.0 op_sel_hi:[1,0]
	v_pk_fma_f32 v[18:19], v[18:19], v[26:27], v[122:123]
	v_pk_fma_f32 v[16:17], v[16:17], v[24:25], v[120:121]
	s_nop 0
	v_cvt_pk_bf16_f32 v16, v16, v17
	v_cvt_pk_bf16_f32 v17, v18, v19
	flat_store_dwordx2 v[20:21], v[16:17] offset:1536
	v_lshl_add_u64 v[20:21], v[20:21], 0, s[4:5]
	s_cbranch_scc0 .LBB0_691
